# in-proj epilogue: nt stores for the q and gate column tiles (each read once by attention); k/v tiles default
# baseline (speedup 1.0000x reference)
; #define PG8_STAGE(bufoff, gbase, voff) do { _Pragma("unroll") for (int _i = 0; _i < 2; ++_i) \
;         __builtin_amdgcn_global_load_lds((const unsigned*)((const char*)(gbase) + (voff)[_i]), (LAS unsigned*)(lds + (bufoff) + ldsw + _i * 8192), 16, 0, 0); } while (0)
; #define PG8_LDA(dst, b, h) do { _Pragma("unroll") for (int m = 0; m < 4; ++m) _Pragma("unroll") for (int k = 0; k < 2; ++k) dst[m][k] = *(const LAS bf16x8*)(lds + PG8_SA(b, h) + aoff + m * 2048 + k * 1024); } while (0)
; #define PG8_LDB(dst, b, h) do { _Pragma("unroll") for (int n = 0; n < 2; ++n) _Pragma("unroll") for (int k = 0; k < 2; ++k) dst[n][k] = *(const LAS bf16x8*)(lds + PG8_SB(b, h) + boff + n * 2048 + k * 1024); } while (0)
; #define PG8_MMA(ai, bj, At, Bt) do { __builtin_amdgcn_s_setprio(1); _Pragma("unroll") for (int m = 0; m < 4; ++m) _Pragma("unroll") for (int n = 0; n < 2; ++n) _Pragma("unroll") for (int k = 0; k < 2; ++k) \
;         acc[ai][bj][m][n] = __builtin_amdgcn_mfma_f32_16x16x32_bf16(Bt[n][k], At[m][k], acc[ai][bj][m][n], 0, 0, 0); __builtin_amdgcn_s_setprio(0); } while (0)
; #define PG8_WAIT_V(n) asm volatile("s_waitcnt vmcnt(" #n ")" ::: "memory")
; #define PG8_WAIT_L(n) asm volatile("s_waitcnt lgkmcnt(" #n ")" ::: "memory")
; #define PG8_BAR __builtin_amdgcn_s_barrier()
; #define PG8_SCHED __builtin_amdgcn_sched_barrier(0)
; template <class Epi>
; DI void gemm_phase(LAS unsigned char* lds, const Gemm g, const StaticOrder& S, const Epi& E, const int tid) {
;     ...
;             PG8_LDB(B0, 0, 0); PG8_SCHED; PG8_LDA(At, 0, 0); PG8_STAGE(PG8_SA(1, 1), a1 + hstepA, voffA);
;             PG8_WAIT_L(8); PG8_BAR; PG8_WAIT_L(0); PG8_MMA(0, 0, At, B0); PG8_BAR; PG8_SCHED;
;             PG8_LDB(B1, 0, 1); PG8_STAGE(PG8_SB(0, 0), b2, voffB);
;             PG8_BAR; PG8_WAIT_L(0); PG8_MMA(0, 1, At, B1); PG8_BAR;
;             PG8_LDA(At, 0, 1); PG8_STAGE(PG8_SA(0, 0), a2, voffA);
;             PG8_BAR; PG8_WAIT_L(0); PG8_MMA(1, 0, At, B0); PG8_BAR; PG8_SCHED;
;             PG8_STAGE(PG8_SB(0, 1), b2 + hstepB, voffB);
;             PG8_WAIT_V(6); PG8_BAR; PG8_MMA(1, 1, At, B1); PG8_BAR;
.LBB0_62:
	s_add_i32 s69, 0, 0x10000
	ds_read_b128 v[158:161], v241
	ds_read_b128 v[162:165], v241 offset:1024
	ds_read_b128 v[166:169], v241 offset:2048
	ds_read_b128 v[178:181], v241 offset:3072
	s_add_i32 m0, s41, 0xc000
	ds_read_b128 v[182:185], v151
	ds_read_b128 v[186:189], v151 offset:1024
	ds_read_b128 v[190:193], v151 offset:2048
	ds_read_b128 v[194:197], v151 offset:3072
	ds_read_b128 v[198:201], v151 offset:4096
	ds_read_b128 v[202:205], v151 offset:5120
	ds_read_b128 v[206:209], v151 offset:6144
	ds_read_b128 v[210:213], v151 offset:7168
	global_load_lds_dwordx4 v138, s[86:87]
	s_add_i32 m0, s41, 0xe000
	s_nop 0
	global_load_lds_dwordx4 v140, s[86:87]
	s_waitcnt lgkmcnt(8)
	s_barrier
	s_waitcnt lgkmcnt(0)
	s_setprio 1
	s_waitcnt lgkmcnt(0)
	v_mfma_f32_16x16x32_bf16 v[126:129], v[158:161], v[182:185], v[126:129]
	v_mfma_f32_16x16x32_bf16 v[122:125], v[166:169], v[182:185], v[122:125]
	v_mfma_f32_16x16x32_bf16 v[118:121], v[158:161], v[190:193], v[118:121]
	v_mfma_f32_16x16x32_bf16 v[114:117], v[166:169], v[190:193], v[114:117]
	v_mfma_f32_16x16x32_bf16 v[102:105], v[158:161], v[198:201], v[102:105]
	v_mfma_f32_16x16x32_bf16 v[98:101], v[166:169], v[198:201], v[98:101]
	v_mfma_f32_16x16x32_bf16 v[86:89], v[158:161], v[206:209], v[86:89]
	v_mfma_f32_16x16x32_bf16 v[82:85], v[166:169], v[206:209], v[82:85]
	v_mfma_f32_16x16x32_bf16 v[126:129], v[162:165], v[186:189], v[126:129]
	v_mfma_f32_16x16x32_bf16 v[122:125], v[178:181], v[186:189], v[122:125]
	v_mfma_f32_16x16x32_bf16 v[118:121], v[162:165], v[194:197], v[118:121]
	v_mfma_f32_16x16x32_bf16 v[114:117], v[178:181], v[194:197], v[114:117]
	v_mfma_f32_16x16x32_bf16 v[102:105], v[162:165], v[202:205], v[102:105]
	v_mfma_f32_16x16x32_bf16 v[98:101], v[178:181], v[202:205], v[98:101]
	v_mfma_f32_16x16x32_bf16 v[86:89], v[162:165], v[210:213], v[86:89]
	v_mfma_f32_16x16x32_bf16 v[82:85], v[178:181], v[210:213], v[82:85]
	s_setprio 0
	s_barrier
	s_add_i32 s78, 0, 0x14000
	s_add_i32 s69, s69, s26
	ds_read_b128 v[214:217], v242
	ds_read_b128 v[218:221], v242 offset:1024
	ds_read_b128 v[222:225], v242 offset:2048
	ds_read_b128 v[226:229], v242 offset:3072
	s_mov_b32 m0, s69
	s_nop 0
	global_load_lds_dwordx4 v0, s[6:7]
	s_add_i32 m0, s69, 0x2000
	s_nop 0
	global_load_lds_dwordx4 v130, s[6:7]
	s_barrier
	s_waitcnt lgkmcnt(0)
	s_setprio 1
	s_waitcnt lgkmcnt(0)
	v_mfma_f32_16x16x32_bf16 v[110:113], v[214:217], v[182:185], v[110:113]
	v_mfma_f32_16x16x32_bf16 v[106:109], v[222:225], v[182:185], v[106:109]
	v_mfma_f32_16x16x32_bf16 v[94:97], v[214:217], v[190:193], v[94:97]
	v_mfma_f32_16x16x32_bf16 v[90:93], v[222:225], v[190:193], v[90:93]
	v_mfma_f32_16x16x32_bf16 v[78:81], v[214:217], v[198:201], v[78:81]
	v_mfma_f32_16x16x32_bf16 v[74:77], v[222:225], v[198:201], v[74:77]
	v_mfma_f32_16x16x32_bf16 v[70:73], v[214:217], v[206:209], v[70:73]
	v_mfma_f32_16x16x32_bf16 v[66:69], v[222:225], v[206:209], v[66:69]
	v_mfma_f32_16x16x32_bf16 v[110:113], v[218:221], v[186:189], v[110:113]
	v_mfma_f32_16x16x32_bf16 v[106:109], v[226:229], v[186:189], v[106:109]
	v_mfma_f32_16x16x32_bf16 v[94:97], v[218:221], v[194:197], v[94:97]
	v_mfma_f32_16x16x32_bf16 v[90:93], v[226:229], v[194:197], v[90:93]
	v_mfma_f32_16x16x32_bf16 v[78:81], v[218:221], v[202:205], v[78:81]
	v_mfma_f32_16x16x32_bf16 v[74:77], v[226:229], v[202:205], v[74:77]
	v_mfma_f32_16x16x32_bf16 v[70:73], v[218:221], v[210:213], v[70:73]
	v_mfma_f32_16x16x32_bf16 v[66:69], v[226:229], v[210:213], v[66:69]
	s_setprio 0
	s_mov_b32 m0, s41
	s_barrier
	ds_read_b128 v[182:185], v151 offset:16384
	ds_read_b128 v[186:189], v151 offset:17408
	ds_read_b128 v[190:193], v151 offset:18432
	ds_read_b128 v[194:197], v151 offset:19456
	ds_read_b128 v[198:201], v151 offset:20480
	ds_read_b128 v[202:205], v151 offset:21504
	ds_read_b128 v[206:209], v151 offset:22528
	ds_read_b128 v[210:213], v151 offset:23552
	global_load_lds_dwordx4 v134, s[50:51]
	s_mov_b32 m0, s55
	s_nop 0
	global_load_lds_dwordx4 v132, s[50:51]
	s_barrier
	s_waitcnt lgkmcnt(0)
	s_setprio 1
	s_waitcnt lgkmcnt(0)
	v_mfma_f32_16x16x32_bf16 v[62:65], v[158:161], v[182:185], v[62:65]
	v_mfma_f32_16x16x32_bf16 v[58:61], v[166:169], v[182:185], v[58:61]
	v_mfma_f32_16x16x32_bf16 v[54:57], v[158:161], v[190:193], v[54:57]
	v_mfma_f32_16x16x32_bf16 v[50:53], v[166:169], v[190:193], v[50:53]
	v_mfma_f32_16x16x32_bf16 v[38:41], v[158:161], v[198:201], v[38:41]
	v_mfma_f32_16x16x32_bf16 v[34:37], v[166:169], v[198:201], v[34:37]
	v_mfma_f32_16x16x32_bf16 v[22:25], v[158:161], v[206:209], v[22:25]
	v_mfma_f32_16x16x32_bf16 v[18:21], v[166:169], v[206:209], v[18:21]
	v_mfma_f32_16x16x32_bf16 v[62:65], v[162:165], v[186:189], v[62:65]
	v_mfma_f32_16x16x32_bf16 v[58:61], v[178:181], v[186:189], v[58:61]
	v_mfma_f32_16x16x32_bf16 v[54:57], v[162:165], v[194:197], v[54:57]
	v_mfma_f32_16x16x32_bf16 v[50:53], v[178:181], v[194:197], v[50:53]
	v_mfma_f32_16x16x32_bf16 v[38:41], v[162:165], v[202:205], v[38:41]
	v_mfma_f32_16x16x32_bf16 v[34:37], v[178:181], v[202:205], v[34:37]
	v_mfma_f32_16x16x32_bf16 v[22:25], v[162:165], v[210:213], v[22:25]
	v_mfma_f32_16x16x32_bf16 v[18:21], v[178:181], v[210:213], v[18:21]
	s_setprio 0
	s_barrier
	s_add_u32 s86, s6, 0x80000
	s_addc_u32 s87, s7, 0
	s_add_i32 s69, s78, s26
	s_mov_b32 m0, s69
	s_nop 0
	global_load_lds_dwordx4 v0, s[86:87]
	s_add_i32 m0, s69, 0x2000
	s_nop 0
	global_load_lds_dwordx4 v130, s[86:87]
	s_waitcnt vmcnt(6)
	s_barrier
; #define PG8_STAGE(bufoff, gbase, voff) do { _Pragma("unroll") for (int _i = 0; _i < 2; ++_i) \
;         __builtin_amdgcn_global_load_lds((const unsigned*)((const char*)(gbase) + (voff)[_i]), (LAS unsigned*)(lds + (bufoff) + ldsw + _i * 8192), 16, 0, 0); } while (0)
; #define PG8_LDA(dst, b, h) do { _Pragma("unroll") for (int m = 0; m < 4; ++m) _Pragma("unroll") for (int k = 0; k < 2; ++k) dst[m][k] = *(const LAS bf16x8*)(lds + PG8_SA(b, h) + aoff + m * 2048 + k * 1024); } while (0)
; #define PG8_LDB(dst, b, h) do { _Pragma("unroll") for (int n = 0; n < 2; ++n) _Pragma("unroll") for (int k = 0; k < 2; ++k) dst[n][k] = *(const LAS bf16x8*)(lds + PG8_SB(b, h) + boff + n * 2048 + k * 1024); } while (0)
; #define PG8_MMA(ai, bj, At, Bt) do { __builtin_amdgcn_s_setprio(1); _Pragma("unroll") for (int m = 0; m < 4; ++m) _Pragma("unroll") for (int n = 0; n < 2; ++n) _Pragma("unroll") for (int k = 0; k < 2; ++k) \
;         acc[ai][bj][m][n] = __builtin_amdgcn_mfma_f32_16x16x32_bf16(Bt[n][k], At[m][k], acc[ai][bj][m][n], 0, 0, 0); __builtin_amdgcn_s_setprio(0); } while (0)
; #define PG8_WAIT_V(n) asm volatile("s_waitcnt vmcnt(" #n ")" ::: "memory")
; #define PG8_WAIT_L(n) asm volatile("s_waitcnt lgkmcnt(" #n ")" ::: "memory")
; #define PG8_BAR __builtin_amdgcn_s_barrier()
; #define PG8_SCHED __builtin_amdgcn_sched_barrier(0)
; template <class Epi>
; DI void gemm_phase(LAS unsigned char* lds, const Gemm g, const StaticOrder& S, const Epi& E, const int tid) {
;     ...
;             PG8_WAIT_V(6); PG8_BAR; PG8_MMA(1, 1, At, B1); PG8_BAR;
;             PG8_LDB(B0, 1, 0); PG8_SCHED; PG8_LDA(At, 1, 0); PG8_STAGE(PG8_SA(0, 1), a2 + hstepA, voffA);
;             PG8_WAIT_L(8); PG8_BAR; PG8_WAIT_L(0); PG8_MMA(0, 0, At, B0); PG8_BAR; PG8_SCHED;
;             PG8_LDB(B1, 1, 1); PG8_STAGE(PG8_SB(1, 0), b3, voffB);
;             PG8_BAR; PG8_WAIT_L(0); PG8_MMA(0, 1, At, B1); PG8_BAR;
;             PG8_LDA(At, 1, 1); PG8_STAGE(PG8_SA(1, 0), a3, voffA);
;             PG8_BAR; PG8_WAIT_L(0); PG8_MMA(1, 0, At, B0); PG8_BAR; PG8_SCHED;
	s_setprio 1
	v_mfma_f32_16x16x32_bf16 v[46:49], v[214:217], v[182:185], v[46:49]
	v_mfma_f32_16x16x32_bf16 v[42:45], v[222:225], v[182:185], v[42:45]
	v_mfma_f32_16x16x32_bf16 v[30:33], v[214:217], v[190:193], v[30:33]
	v_mfma_f32_16x16x32_bf16 v[26:29], v[222:225], v[190:193], v[26:29]
	v_mfma_f32_16x16x32_bf16 v[14:17], v[214:217], v[198:201], v[14:17]
	v_mfma_f32_16x16x32_bf16 v[10:13], v[222:225], v[198:201], v[10:13]
	v_mfma_f32_16x16x32_bf16 v[6:9], v[214:217], v[206:209], v[6:9]
	v_mfma_f32_16x16x32_bf16 v[2:5], v[222:225], v[206:209], v[2:5]
	v_mfma_f32_16x16x32_bf16 v[46:49], v[218:221], v[186:189], v[46:49]
	v_mfma_f32_16x16x32_bf16 v[42:45], v[226:229], v[186:189], v[42:45]
	v_mfma_f32_16x16x32_bf16 v[30:33], v[218:221], v[194:197], v[30:33]
	v_mfma_f32_16x16x32_bf16 v[26:29], v[226:229], v[194:197], v[26:29]
	v_mfma_f32_16x16x32_bf16 v[14:17], v[218:221], v[202:205], v[14:17]
	v_mfma_f32_16x16x32_bf16 v[10:13], v[226:229], v[202:205], v[10:13]
	v_mfma_f32_16x16x32_bf16 v[6:9], v[218:221], v[210:213], v[6:9]
	v_mfma_f32_16x16x32_bf16 v[2:5], v[226:229], v[210:213], v[2:5]
	s_setprio 0
	s_add_i32 s69, 0, 0x18000
	s_barrier
	ds_read_b128 v[158:161], v243
	ds_read_b128 v[162:165], v243 offset:1024
	ds_read_b128 v[166:169], v243 offset:2048
	ds_read_b128 v[178:181], v243 offset:3072
	s_add_u32 s50, s50, 0x80000
	s_addc_u32 s51, s51, 0
	s_mov_b32 m0, s56
	s_nop 0
	ds_read_b128 v[182:185], v151 offset:32768
	ds_read_b128 v[186:189], v151 offset:33792
	ds_read_b128 v[190:193], v151 offset:34816
	ds_read_b128 v[194:197], v151 offset:35840
	ds_read_b128 v[198:201], v151 offset:36864
	ds_read_b128 v[202:205], v151 offset:37888
	ds_read_b128 v[206:209], v151 offset:38912
	ds_read_b128 v[210:213], v151 offset:39936
	global_load_lds_dwordx4 v134, s[50:51]
	s_mov_b32 m0, s57
	s_nop 0
	global_load_lds_dwordx4 v132, s[50:51]
	s_waitcnt lgkmcnt(8)
	s_barrier
	s_waitcnt lgkmcnt(0)
	s_setprio 1
	s_waitcnt lgkmcnt(0)
	v_mfma_f32_16x16x32_bf16 v[126:129], v[158:161], v[182:185], v[126:129]
	v_mfma_f32_16x16x32_bf16 v[122:125], v[166:169], v[182:185], v[122:125]
	v_mfma_f32_16x16x32_bf16 v[118:121], v[158:161], v[190:193], v[118:121]
	v_mfma_f32_16x16x32_bf16 v[114:117], v[166:169], v[190:193], v[114:117]
	v_mfma_f32_16x16x32_bf16 v[102:105], v[158:161], v[198:201], v[102:105]
	v_mfma_f32_16x16x32_bf16 v[98:101], v[166:169], v[198:201], v[98:101]
	v_mfma_f32_16x16x32_bf16 v[86:89], v[158:161], v[206:209], v[86:89]
	v_mfma_f32_16x16x32_bf16 v[82:85], v[166:169], v[206:209], v[82:85]
	v_mfma_f32_16x16x32_bf16 v[126:129], v[162:165], v[186:189], v[126:129]
	v_mfma_f32_16x16x32_bf16 v[122:125], v[178:181], v[186:189], v[122:125]
	v_mfma_f32_16x16x32_bf16 v[118:121], v[162:165], v[194:197], v[118:121]
	v_mfma_f32_16x16x32_bf16 v[114:117], v[178:181], v[194:197], v[114:117]
	v_mfma_f32_16x16x32_bf16 v[102:105], v[162:165], v[202:205], v[102:105]
	v_mfma_f32_16x16x32_bf16 v[98:101], v[178:181], v[202:205], v[98:101]
	v_mfma_f32_16x16x32_bf16 v[86:89], v[162:165], v[210:213], v[86:89]
	v_mfma_f32_16x16x32_bf16 v[82:85], v[178:181], v[210:213], v[82:85]
	s_setprio 0
	s_barrier
	s_add_i32 s50, 0, 0x1c000
	s_add_i32 s51, s69, s26
	s_add_u32 s86, s6, s84
	s_addc_u32 s87, s7, s85
	s_mov_b32 m0, s51
	ds_read_b128 v[214:217], v244
	ds_read_b128 v[218:221], v244 offset:1024
	ds_read_b128 v[222:225], v244 offset:2048
	ds_read_b128 v[226:229], v244 offset:3072
	global_load_lds_dwordx4 v0, s[86:87]
	s_add_i32 m0, s51, 0x2000
	s_nop 0
	global_load_lds_dwordx4 v130, s[86:87]
	s_barrier
	s_waitcnt lgkmcnt(0)
	s_setprio 1
	s_waitcnt lgkmcnt(0)
	v_mfma_f32_16x16x32_bf16 v[110:113], v[214:217], v[182:185], v[110:113]
	v_mfma_f32_16x16x32_bf16 v[106:109], v[222:225], v[182:185], v[106:109]
	v_mfma_f32_16x16x32_bf16 v[94:97], v[214:217], v[190:193], v[94:97]
	v_mfma_f32_16x16x32_bf16 v[90:93], v[222:225], v[190:193], v[90:93]
	v_mfma_f32_16x16x32_bf16 v[78:81], v[214:217], v[198:201], v[78:81]
	v_mfma_f32_16x16x32_bf16 v[74:77], v[222:225], v[198:201], v[74:77]
	v_mfma_f32_16x16x32_bf16 v[70:73], v[214:217], v[206:209], v[70:73]
	v_mfma_f32_16x16x32_bf16 v[66:69], v[222:225], v[206:209], v[66:69]
	v_mfma_f32_16x16x32_bf16 v[110:113], v[218:221], v[186:189], v[110:113]
	v_mfma_f32_16x16x32_bf16 v[106:109], v[226:229], v[186:189], v[106:109]
	v_mfma_f32_16x16x32_bf16 v[94:97], v[218:221], v[194:197], v[94:97]
	v_mfma_f32_16x16x32_bf16 v[90:93], v[226:229], v[194:197], v[90:93]
	v_mfma_f32_16x16x32_bf16 v[78:81], v[218:221], v[202:205], v[78:81]
	v_mfma_f32_16x16x32_bf16 v[74:77], v[226:229], v[202:205], v[74:77]
	v_mfma_f32_16x16x32_bf16 v[70:73], v[218:221], v[210:213], v[70:73]
	v_mfma_f32_16x16x32_bf16 v[66:69], v[226:229], v[210:213], v[66:69]
	s_setprio 0
	s_mov_b32 m0, s59
	s_nop 0
	s_barrier
	ds_read_b128 v[182:185], v151 offset:49152
	ds_read_b128 v[186:189], v151 offset:50176
	ds_read_b128 v[190:193], v151 offset:51200
	ds_read_b128 v[194:197], v151 offset:52224
	ds_read_b128 v[198:201], v151 offset:53248
	ds_read_b128 v[202:205], v151 offset:54272
	ds_read_b128 v[206:209], v151 offset:55296
	ds_read_b128 v[210:213], v151 offset:56320
	global_load_lds_dwordx4 v134, s[8:9]
	s_mov_b32 m0, s60
	s_nop 0
	global_load_lds_dwordx4 v132, s[8:9]
	s_barrier
; #define PG8_STAGE(bufoff, gbase, voff) do { _Pragma("unroll") for (int _i = 0; _i < 2; ++_i) \
;         __builtin_amdgcn_global_load_lds((const unsigned*)((const char*)(gbase) + (voff)[_i]), (LAS unsigned*)(lds + (bufoff) + ldsw + _i * 8192), 16, 0, 0); } while (0)
; #define PG8_MMA(ai, bj, At, Bt) do { __builtin_amdgcn_s_setprio(1); _Pragma("unroll") for (int m = 0; m < 4; ++m) _Pragma("unroll") for (int n = 0; n < 2; ++n) _Pragma("unroll") for (int k = 0; k < 2; ++k) \
;         acc[ai][bj][m][n] = __builtin_amdgcn_mfma_f32_16x16x32_bf16(Bt[n][k], At[m][k], acc[ai][bj][m][n], 0, 0, 0); __builtin_amdgcn_s_setprio(0); } while (0)
; #define PG8_WAIT_V(n) asm volatile("s_waitcnt vmcnt(" #n ")" ::: "memory")
; #define PG8_WAIT_L(n) asm volatile("s_waitcnt lgkmcnt(" #n ")" ::: "memory")
; #define PG8_BAR __builtin_amdgcn_s_barrier()
; #define PG8_SCHED __builtin_amdgcn_sched_barrier(0)
; template <class Epi>
; DI void gemm_phase(LAS unsigned char* lds, const Gemm g, const StaticOrder& S, const Epi& E, const int tid) {
;     ...
;             PG8_BAR; PG8_WAIT_L(0); PG8_MMA(1, 0, At, B0); PG8_BAR; PG8_SCHED;
;             PG8_STAGE(PG8_SB(1, 1), b3 + hstepB, voffB);
;             PG8_WAIT_V(6); PG8_BAR; PG8_MMA(1, 1, At, B1); PG8_BAR;
;         }
;         E(acc, cur, wr, wc, fr, fq);
;         if (!has_next) break;
	s_waitcnt lgkmcnt(0)
	s_setprio 1
	s_waitcnt lgkmcnt(0)
	v_mfma_f32_16x16x32_bf16 v[62:65], v[158:161], v[182:185], v[62:65]
	v_mfma_f32_16x16x32_bf16 v[58:61], v[166:169], v[182:185], v[58:61]
	v_mfma_f32_16x16x32_bf16 v[54:57], v[158:161], v[190:193], v[54:57]
	v_mfma_f32_16x16x32_bf16 v[50:53], v[166:169], v[190:193], v[50:53]
	v_mfma_f32_16x16x32_bf16 v[38:41], v[158:161], v[198:201], v[38:41]
	v_mfma_f32_16x16x32_bf16 v[34:37], v[166:169], v[198:201], v[34:37]
	v_mfma_f32_16x16x32_bf16 v[22:25], v[158:161], v[206:209], v[22:25]
	v_mfma_f32_16x16x32_bf16 v[18:21], v[166:169], v[206:209], v[18:21]
	v_mfma_f32_16x16x32_bf16 v[62:65], v[162:165], v[186:189], v[62:65]
	v_mfma_f32_16x16x32_bf16 v[58:61], v[178:181], v[186:189], v[58:61]
	v_mfma_f32_16x16x32_bf16 v[54:57], v[162:165], v[194:197], v[54:57]
	v_mfma_f32_16x16x32_bf16 v[50:53], v[178:181], v[194:197], v[50:53]
	v_mfma_f32_16x16x32_bf16 v[38:41], v[162:165], v[202:205], v[38:41]
	v_mfma_f32_16x16x32_bf16 v[34:37], v[178:181], v[202:205], v[34:37]
	v_mfma_f32_16x16x32_bf16 v[22:25], v[162:165], v[210:213], v[22:25]
	v_mfma_f32_16x16x32_bf16 v[18:21], v[178:181], v[210:213], v[18:21]
	s_setprio 0
	s_barrier
	s_add_u32 s6, s6, 0x80080
	s_addc_u32 s7, s7, 0
	s_add_i32 s8, s50, s26
	s_mov_b32 m0, s8
	s_nop 0
	global_load_lds_dwordx4 v0, s[6:7]
	s_add_i32 m0, s8, 0x2000
	s_nop 0
	global_load_lds_dwordx4 v130, s[6:7]
	s_waitcnt vmcnt(6)
	s_barrier
	s_setprio 1
	v_mfma_f32_16x16x32_bf16 v[46:49], v[214:217], v[182:185], v[46:49]
	v_mfma_f32_16x16x32_bf16 v[42:45], v[222:225], v[182:185], v[42:45]
	v_mfma_f32_16x16x32_bf16 v[30:33], v[214:217], v[190:193], v[30:33]
	v_mfma_f32_16x16x32_bf16 v[26:29], v[222:225], v[190:193], v[26:29]
	v_mfma_f32_16x16x32_bf16 v[14:17], v[214:217], v[198:201], v[14:17]
	v_mfma_f32_16x16x32_bf16 v[10:13], v[222:225], v[198:201], v[10:13]
	v_mfma_f32_16x16x32_bf16 v[6:9], v[214:217], v[206:209], v[6:9]
	v_mfma_f32_16x16x32_bf16 v[2:5], v[222:225], v[206:209], v[2:5]
	v_mfma_f32_16x16x32_bf16 v[46:49], v[218:221], v[186:189], v[46:49]
	v_mfma_f32_16x16x32_bf16 v[42:45], v[226:229], v[186:189], v[42:45]
	v_mfma_f32_16x16x32_bf16 v[30:33], v[218:221], v[194:197], v[30:33]
	v_mfma_f32_16x16x32_bf16 v[26:29], v[226:229], v[194:197], v[26:29]
	v_mfma_f32_16x16x32_bf16 v[14:17], v[218:221], v[202:205], v[14:17]
	v_mfma_f32_16x16x32_bf16 v[10:13], v[226:229], v[202:205], v[10:13]
	v_mfma_f32_16x16x32_bf16 v[6:9], v[218:221], v[210:213], v[6:9]
	v_mfma_f32_16x16x32_bf16 v[2:5], v[226:229], v[210:213], v[2:5]
	s_setprio 0
	s_add_i32 s68, s68, 2
	s_add_u32 s4, s4, 0x100
	s_addc_u32 s5, s5, 0
	s_add_u32 s6, s44, s4
	s_addc_u32 s7, s45, s5
	s_add_u32 s8, s6, 0x100
	s_addc_u32 s9, s7, 0
	s_add_u32 s69, s66, s4
	s_addc_u32 s78, s67, s5
	s_add_u32 s86, s6, 0x180
	s_addc_u32 s87, s7, 0
	s_cmpk_eq_i32 s4, 0xf00
	s_cselect_b32 s51, s30, s9
	s_cselect_b32 s50, s31, s8
	s_cselect_b32 s7, s39, s78
	s_cselect_b32 s6, s43, s69
	s_cselect_b32 s9, s65, s87
	s_cselect_b32 s8, s64, s86
	s_add_u32 s86, s44, s4
	s_addc_u32 s87, s45, s5
	s_add_u32 s86, s86, 0x80080
	s_addc_u32 s87, s87, 0
	s_cmp_gt_u32 s68, 29
	s_barrier
	s_cbranch_scc0 .LBB0_62
	s_cmpk_eq_i32 s58, 18
	s_cselect_b32 s4, 10, 24
	s_cmp_ge_u32 s63, s4
	s_cbranch_scc1 .Lepi_gate
	s_cmp_lt_u32 s63, 8
	s_cbranch_scc1 .Lepi_gate
; DI unsigned pk2(float a, float b) { f32x2 v = {a, b}; bf16v2 r = __builtin_convertvector(v, bf16v2); return __builtin_bit_cast(unsigned, r); }
;     DI void operator()(const f32x4 (&acc)[2][2][4][2], const Unit& u, int wr, int wc, int fr, int fq) const {
;     ...
;             unsigned char* tb = (unsigned char*)O + ((size_t)(u.pm * nt + u.pn) << 17) + (wr * 4 + wc) * 1024 + (fq * 16 + fr) * 16;
; #pragma unroll
;             for (int ai = 0; ai < 2; ++ai)
; #pragma unroll
;                 for (int m = 0; m < 4; ++m)
; #pragma unroll
;                     for (int bj = 0; bj < 2; ++bj) { const f32x4 v0 = acc[ai][bj][m][0], v1 = acc[ai][bj][m][1];
;                         u32x4 w; w.x = pk2(v0[0], v0[1]); w.y = pk2(v0[2], v0[3]); w.z = pk2(v1[0], v1[1]); w.w = pk2(v1[2], v1[3]);
;                         *(u32x4*)(tb + ((ai * 4 + m) * 2 + bj) * 8192) = w; }
; template <class Epi>
; DI void gemm_phase(LAS unsigned char* lds, const Gemm g, const StaticOrder& S, const Epi& E, const int tid) {
;     ...
;         if (!has_next) break;
; #pragma unroll
;         for (int a = 0; a < 2; ++a)
; #pragma unroll
;             for (int b = 0; b < 2; ++b)
; #pragma unroll
;                 for (int m = 0; m < 4; ++m)
; #pragma unroll
;                     for (int n = 0; n < 2; ++n) acc[a][b][m][n] = (f32x4){0.f, 0.f, 0.f, 0.f};
;         cur = nxt; cA = nA; cB = nB; ++ui;
	s_mul_i32 s4, s40, s58
	s_add_i32 s4, s4, s63
	s_ashr_i32 s5, s4, 31
	s_lshl_b64 s[4:5], s[4:5], 17
	v_lshl_add_u64 v[144:145], v[136:137], 0, s[4:5]
	s_movk_i32 s4, 0x2000
	v_cvt_pk_bf16_f32 v110, v110, v111
	v_cvt_pk_bf16_f32 v111, v112, v113
	v_cvt_pk_bf16_f32 v112, v106, v107
	v_add_co_u32_e32 v106, vcc, s4, v144
	v_cvt_pk_bf16_f32 v113, v108, v109
	s_nop 0
	v_addc_co_u32_e32 v107, vcc, 0, v145, vcc
	global_store_dwordx4 v[106:107], v[110:113], off
	s_movk_i32 s4, 0x6000
	v_cvt_pk_bf16_f32 v94, v94, v95
	v_add_co_u32_e32 v110, vcc, s3, v144
	v_cvt_pk_bf16_f32 v95, v96, v97
	s_nop 0
	v_addc_co_u32_e32 v111, vcc, 0, v145, vcc
	v_cvt_pk_bf16_f32 v96, v90, v91
	v_add_co_u32_e32 v90, vcc, s4, v144
	v_cvt_pk_bf16_f32 v97, v92, v93
	s_nop 0
	v_addc_co_u32_e32 v91, vcc, 0, v145, vcc
	s_mov_b32 s4, 0x8000
	global_store_dwordx4 v[90:91], v[94:97], off
	v_cvt_pk_bf16_f32 v78, v78, v79
	v_cvt_pk_bf16_f32 v79, v80, v81
	v_add_co_u32_e32 v94, vcc, s4, v144
	s_mov_b32 s4, 0xa000
	s_nop 0
	v_addc_co_u32_e32 v95, vcc, 0, v145, vcc
	v_cvt_pk_bf16_f32 v80, v74, v75
	v_add_co_u32_e32 v74, vcc, s4, v144
	v_cvt_pk_bf16_f32 v81, v76, v77
	s_nop 0
	v_addc_co_u32_e32 v75, vcc, 0, v145, vcc
	global_store_dwordx4 v[74:75], v[78:81], off
	s_mov_b32 s4, 0xe000
	v_cvt_pk_bf16_f32 v70, v70, v71
	v_add_co_u32_e32 v78, vcc, s13, v144
	v_cvt_pk_bf16_f32 v71, v72, v73
	s_nop 0
	v_addc_co_u32_e32 v79, vcc, 0, v145, vcc
	v_cvt_pk_bf16_f32 v72, v66, v67
	v_add_co_u32_e32 v66, vcc, s4, v144
	s_mov_b32 s4, 0x10000
	s_nop 0
	v_addc_co_u32_e32 v67, vcc, 0, v145, vcc
	v_cvt_pk_bf16_f32 v62, v62, v63
	v_cvt_pk_bf16_f32 v63, v64, v65
	v_cvt_pk_bf16_f32 v64, v58, v59
	v_add_co_u32_e32 v58, vcc, s4, v144
	s_mov_b32 s4, 0x12000
	s_nop 0
	v_addc_co_u32_e32 v59, vcc, 0, v145, vcc
	v_cvt_pk_bf16_f32 v46, v46, v47
	v_cvt_pk_bf16_f32 v47, v48, v49
	v_cvt_pk_bf16_f32 v48, v42, v43
	v_add_co_u32_e32 v42, vcc, s4, v144
	v_cvt_pk_bf16_f32 v49, v44, v45
	s_nop 0
	v_addc_co_u32_e32 v43, vcc, 0, v145, vcc
	s_mov_b32 s4, 0x14000
	global_store_dwordx4 v[42:43], v[46:49], off
	v_cvt_pk_bf16_f32 v30, v30, v31
	v_cvt_pk_bf16_f32 v31, v32, v33
	v_add_co_u32_e32 v46, vcc, s4, v144
	s_mov_b32 s4, 0x16000
	s_nop 0
	v_addc_co_u32_e32 v47, vcc, 0, v145, vcc
	v_cvt_pk_bf16_f32 v32, v26, v27
	v_add_co_u32_e32 v26, vcc, s4, v144
	v_cvt_pk_bf16_f32 v33, v28, v29
	s_nop 0
	v_addc_co_u32_e32 v27, vcc, 0, v145, vcc
	s_mov_b32 s4, 0x18000
	global_store_dwordx4 v[26:27], v[30:33], off
	v_cvt_pk_bf16_f32 v14, v14, v15
	v_cvt_pk_bf16_f32 v15, v16, v17
	v_add_co_u32_e32 v30, vcc, s4, v144
	s_mov_b32 s4, 0x1a000
	s_nop 0
	v_addc_co_u32_e32 v31, vcc, 0, v145, vcc
	v_cvt_pk_bf16_f32 v16, v10, v11
	v_add_co_u32_e32 v10, vcc, s4, v144
	v_cvt_pk_bf16_f32 v17, v12, v13
	s_nop 0
	v_addc_co_u32_e32 v11, vcc, 0, v145, vcc
	s_mov_b32 s4, 0x1c000
	global_store_dwordx4 v[10:11], v[14:17], off
	v_cvt_pk_bf16_f32 v6, v6, v7
	v_cvt_pk_bf16_f32 v7, v8, v9
	v_add_co_u32_e32 v14, vcc, s4, v144
	v_cvt_pk_bf16_f32 v8, v2, v3
	s_nop 0
	v_addc_co_u32_e32 v15, vcc, 0, v145, vcc
	v_add_co_u32_e32 v2, vcc, 0x1e000, v144
	v_cvt_pk_bf16_f32 v126, v126, v127
	s_nop 0
	v_addc_co_u32_e32 v3, vcc, 0, v145, vcc
	v_cvt_pk_bf16_f32 v127, v128, v129
	v_cvt_pk_bf16_f32 v128, v122, v123
	v_cvt_pk_bf16_f32 v129, v124, v125
	v_cvt_pk_bf16_f32 v106, v118, v119
	v_cvt_pk_bf16_f32 v107, v120, v121
	v_cvt_pk_bf16_f32 v108, v114, v115
	v_cvt_pk_bf16_f32 v109, v116, v117
	v_cvt_pk_bf16_f32 v90, v102, v103
	v_cvt_pk_bf16_f32 v91, v104, v105
	v_cvt_pk_bf16_f32 v92, v98, v99
	v_cvt_pk_bf16_f32 v93, v100, v101
	v_cvt_pk_bf16_f32 v74, v86, v87
	v_cvt_pk_bf16_f32 v75, v88, v89
	v_cvt_pk_bf16_f32 v76, v82, v83
	v_cvt_pk_bf16_f32 v77, v84, v85
	v_cvt_pk_bf16_f32 v73, v68, v69
	v_cvt_pk_bf16_f32 v65, v60, v61
	v_cvt_pk_bf16_f32 v42, v54, v55
	v_cvt_pk_bf16_f32 v43, v56, v57
	v_cvt_pk_bf16_f32 v44, v50, v51
	v_cvt_pk_bf16_f32 v45, v52, v53
	v_cvt_pk_bf16_f32 v26, v38, v39
	v_cvt_pk_bf16_f32 v27, v40, v41
	v_cvt_pk_bf16_f32 v28, v34, v35
	v_cvt_pk_bf16_f32 v29, v36, v37
	v_cvt_pk_bf16_f32 v10, v22, v23
	v_cvt_pk_bf16_f32 v11, v24, v25
	v_cvt_pk_bf16_f32 v12, v18, v19
	v_cvt_pk_bf16_f32 v13, v20, v21
	v_cvt_pk_bf16_f32 v9, v4, v5
	s_and_b64 vcc, exec, s[34:35]
	s_mov_b32 s63, s38
	s_mov_b32 s40, s42
	s_mov_b64 s[4:5], s[48:49]
	s_mov_b64 s[44:45], s[46:47]
	global_store_dwordx4 v[144:145], v[126:129], off
	global_store_dwordx4 v[110:111], v[106:109], off
	global_store_dwordx4 v[94:95], v[90:93], off
	global_store_dwordx4 v[78:79], v[74:77], off
	global_store_dwordx4 v[66:67], v[70:73], off
	global_store_dwordx4 v[58:59], v[62:65], off
	global_store_dwordx4 v[46:47], v[42:45], off
	global_store_dwordx4 v[30:31], v[26:29], off
	global_store_dwordx4 v[14:15], v[10:13], off
	global_store_dwordx4 v[2:3], v[6:9], off
	s_cbranch_vccz .LBB0_59
	s_branch .Lepi_done
